# adds: gate pre-activations read x with four 16-byte loads per row pair (lane owns 16 consecutive columns, LDS weight image re-indexed to match) instead of 32 two-byte loads
# speedup vs baseline: 1.0027x; 1.0027x over previous
; __device__ __forceinline__ int opaque_tid() { int t = threadIdx.x; asm volatile("" : "+v"(t)); return t; }
; #define LAS __attribute__((address_space(3)))
; DI void gates_phase(LAS unsigned char* lds, const bf16_t* X, const ss_t* ss, const float* win  , const float* ng, const float* gbias, float* GATES, int G, int bid) {
;     const int tid = opaque_tid(), lane = tid & 63, gw = bid * 8 + (tid >> 6), NGW = G * 8;
;     LAS float* wg = (LAS float*)lds;
;     __syncthreads();
;     for (int k = tid; k < 1024; k += 512) { const float gv = ng[k]; const f32x4 a = *(const f32x4*)(win + (size_t)k * 3080 + 3072), b = *(const f32x4*)(win + (size_t)k * 3080 + 3076);
;         *(LAS f32x4*)(wg + k * 8) = a * gv; *(LAS f32x4*)(wg + k * 8 + 4) = b * gv; }
;     __syncthreads();
;     for (int m0 = gw; m0 < T_ALL; m0 += 2 * NGW) {
;         float acc[2][8];
; #pragma unroll
;         for (int r = 0; r < 2; ++r)
; #pragma unroll
;             for (int j = 0; j < 8; ++j) acc[r][j] = 0.f;
;         const bf16_t* xr0 = X + (size_t)m0 * 1024; const bf16_t* xr1 = X + (size_t)(m0 + NGW) * 1024;
; #pragma unroll 4
;         for (int i = 0; i < 16; ++i) { const int k = lane + 64 * i; const float x0 = __builtin_bit_cast(float, (unsigned)xr0[k] << 16), x1 = __builtin_bit_cast(float, (unsigned)xr1[k] << 16); const f32x4 a = *(const LAS f32x4*)(wg + k * 8), b = *(const LAS f32x4*)(wg + k * 8 + 4);
.LBB0_437:
	v_readlane_b32 s0, v250, 32
	s_cmp_lg_u32 s0, 7
	s_cbranch_scc1 .LBB0_455
	v_mov_b32_e32 v2, v226
	s_movk_i32 s0, 0x400
	s_waitcnt vmcnt(0) lgkmcnt(0)
	v_cmp_gt_i32_e32 vcc, s0, v2
	s_barrier
	s_and_saveexec_b64 s[0:1], vcc
	s_movk_i32 s42, 0x1ff
	s_cbranch_execz .LBB0_441
	v_readlane_b32 s38, v250, 28
	v_readlane_b32 s39, v250, 29
	s_mov_b32 s87, s35
	s_mul_hi_u32 s2, s38, 0xc08000
	s_mul_i32 s34, s38, 0xc08000
	s_lshl_b64 s[38:39], s[86:87], 12
	s_add_u32 s38, s6, s38
	v_ashrrev_i32_e32 v3, 31, v2
	s_addc_u32 s39, s7, s39
	v_lshl_add_u64 v[0:1], v[2:3], 2, s[38:39]
	v_readlane_b32 s38, v251, 38
	s_add_u32 s38, s38, s34
	v_readlane_b32 s34, v251, 55
	s_addc_u32 s39, s34, s2
	v_mov_b64_e32 v[4:5], s[38:39]
	s_movk_i32 s2, 0x3020
	v_mad_i64_i32 v[4:5], s[38:39], v2, s2, v[4:5]
	v_add_u32_e32 v6, 0xfffffe00, v2
	v_and_b32_e32 v7, 15, v2
	v_lshrrev_b32_e32 v3, 4, v2
	v_lshlrev_b32_e32 v7, 11, v7
	v_lshl_add_u32 v7, v3, 5, v7
	s_mov_b64 s[38:39], 0
.LBB0_440:
	global_load_dword v16, v[0:1], off
	global_load_dwordx4 v[8:11], v[4:5], off
	global_load_dwordx4 v[12:15], v[4:5], off offset:16
	v_add_u32_e32 v6, 0x200, v6
	s_mov_b64 s[40:41], 0x800
	v_lshl_add_u64 v[0:1], v[0:1], 0, s[40:41]
	s_mov_b64 s[40:41], 0x604000
	v_cmp_lt_i32_e32 vcc, s42, v6
	v_lshl_add_u64 v[4:5], v[4:5], 0, s[40:41]
	s_or_b64 s[38:39], vcc, s[38:39]
	s_waitcnt vmcnt(1)
	v_pk_mul_f32 v[10:11], v[10:11], v[16:17] op_sel_hi:[1,0]
	v_pk_mul_f32 v[8:9], v[8:9], v[16:17] op_sel_hi:[1,0]
	s_waitcnt vmcnt(0)
	v_pk_mul_f32 v[14:15], v[14:15], v[16:17] op_sel_hi:[1,0]
	v_pk_mul_f32 v[12:13], v[12:13], v[16:17] op_sel_hi:[1,0]
	ds_write_b128 v7, v[8:11]
	ds_write_b128 v7, v[12:15] offset:16
	v_add_u32_e32 v7, 0x400, v7
	s_andn2_b64 exec, exec, s[38:39]
	s_cbranch_execnz .LBB0_440
.LBB0_441:
	s_or_b64 exec, exec, s[0:1]
	v_ashrrev_i32_e32 v1, 6, v2
	v_readlane_b32 s0, v251, 58
	s_waitcnt lgkmcnt(0)
	s_barrier
	v_add_u32_e32 v0, s0, v1
	s_mov_b32 s0, 0x8000
	v_cmp_gt_i32_e32 vcc, s0, v0
	s_and_saveexec_b64 s[46:47], vcc
	s_cbranch_execz .LBB0_454
	s_lshl_b32 s34, s86, 1
	s_lshl_b64 s[0:1], s[34:35], 18
	s_add_u32 s48, s88, s0
	s_addc_u32 s49, s89, s1
	v_readlane_b32 s0, v250, 28
	v_readlane_b32 s1, v250, 29
	s_lshl_b32 s34, s0, 3
	v_readlane_b32 s52, v251, 39
	s_lshl_b64 s[0:1], s[34:35], 2
	v_readlane_b32 s54, v251, 41
	v_and_b32_e32 v3, 1, v2
	v_and_b32_e32 v4, 64, v232
	v_readlane_b32 s55, v251, 42
	s_add_u32 s44, s54, s0
	v_cmp_eq_u32_e32 vcc, 0, v3
	v_xor_b32_e32 v3, 1, v232
	v_add_u32_e32 v4, 64, v4
	s_addc_u32 s45, s55, s1
	v_cmp_lt_i32_e64 s[0:1], v3, v4
	v_and_b32_e32 v8, 63, v2
	v_cmp_gt_u32_e64 s[42:43], 8, v8
	v_cndmask_b32_e64 v3, v232, v3, s[0:1]
	v_lshlrev_b32_e32 v26, 2, v3
	v_and_b32_e32 v3, 2, v2
	v_cmp_eq_u32_e64 s[38:39], 0, v3
	v_xor_b32_e32 v3, 2, v232
	v_cmp_lt_i32_e64 s[0:1], v3, v4
	v_lshl_add_u32 v32, v8, 5, 0
	v_lshlrev_b32_e32 v10, 5, v8
	v_cndmask_b32_e64 v3, v232, v3, s[0:1]
	v_lshlrev_b32_e32 v27, 2, v3
	v_and_b32_e32 v3, 4, v2
	v_cmp_eq_u32_e64 s[40:41], 0, v3
	v_xor_b32_e32 v3, 4, v232
	v_cmp_lt_i32_e64 s[0:1], v3, v4
	v_bfrev_b32_e32 v2, v2
	s_mov_b64 s[50:51], 0
	v_cndmask_b32_e64 v3, v232, v3, s[0:1]
	v_lshlrev_b32_e32 v28, 2, v3
	v_xor_b32_e32 v3, 8, v232
	v_cmp_lt_i32_e64 s[0:1], v3, v4
	v_readlane_b32 s53, v251, 40
	v_readlane_b32 s56, v251, 43
	v_cndmask_b32_e64 v3, v232, v3, s[0:1]
	v_lshlrev_b32_e32 v29, 2, v3
	v_xor_b32_e32 v3, 16, v232
	v_cmp_lt_i32_e64 s[0:1], v3, v4
	v_readlane_b32 s57, v251, 44
	v_readlane_b32 s58, v251, 45
	v_cndmask_b32_e64 v3, v232, v3, s[0:1]
	v_lshlrev_b32_e32 v30, 2, v3
	v_xor_b32_e32 v3, 32, v232
	v_cmp_lt_i32_e64 s[0:1], v3, v4
	v_ashrrev_i16_sdwa v4, v235, v2 dst_sel:DWORD dst_unused:UNUSED_PAD src0_sel:DWORD src1_sel:WORD_1
	v_lshrrev_b32_e32 v2, 27, v2
	v_cndmask_b32_e64 v3, v232, v3, s[0:1]
	v_readlane_b32 s0, v251, 59
	v_and_b32_e32 v112, 28, v2
	v_lshlrev_b32_e32 v31, 2, v3
	v_add_u32_e32 v6, s0, v1
	v_ashrrev_i32_e32 v7, 31, v6
	v_ashrrev_i32_e32 v1, 31, v0
	v_lshlrev_b64 v[6:7], 11, v[6:7]
	v_readlane_b32 s0, v251, 56
	v_lshlrev_b64 v[8:9], 11, v[0:1]
	v_or_b32_e32 v6, v6, v10
	v_readlane_b32 s1, v251, 57
	v_or_b32_e32 v8, v8, v10
	v_lshl_add_u64 v[2:3], s[44:45], 0, v[112:113]
	v_cmp_gt_i16_e64 s[44:45], 0, v4
	v_lshl_add_u64 v[4:5], s[90:91], 0, v[112:113]
	v_lshl_add_u64 v[6:7], s[0:1], 0, v[6:7]
	v_lshl_add_u64 v[8:9], s[0:1], 0, v[8:9]
	v_readlane_b32 s59, v251, 46
	v_readlane_b32 s60, v251, 47
	v_readlane_b32 s61, v251, 48
	v_readlane_b32 s62, v251, 49
	v_readlane_b32 s63, v251, 50
	v_readlane_b32 s64, v251, 51
	v_readlane_b32 s65, v251, 52
	v_readlane_b32 s66, v251, 53
	v_readlane_b32 s67, v251, 54
	s_branch .LBB0_445

; #define LAS __attribute__((address_space(3)))
; DI void gates_phase(LAS unsigned char* lds, const bf16_t* X, const ss_t* ss, const float* win  , const float* ng, const float* gbias, float* GATES, int G, int bid) {
;     ...
;         const bf16_t* xr0 = X + (size_t)m0 * 1024; const bf16_t* xr1 = X + (size_t)(m0 + NGW) * 1024;
; #pragma unroll 4
;         for (int i = 0; i < 16; ++i) { const int k = lane + 64 * i; const float x0 = __builtin_bit_cast(float, (unsigned)xr0[k] << 16), x1 = __builtin_bit_cast(float, (unsigned)xr1[k] << 16); const f32x4 a = *(const LAS f32x4*)(wg + k * 8), b = *(const LAS f32x4*)(wg + k * 8 + 4);
; #pragma unroll
;             for (int e = 0; e < 4; ++e) { acc[0][e] += x0 * a[e]; acc[0][4 + e] += x0 * b[e]; acc[1][e] += x1 * a[e]; acc[1][4 + e] += x1 * b[e]; } }
.LBB0_446:
	v_mov_b32_e32 v84, v0
	v_ashrrev_i32_e32 v85, 31, v0
	v_add_u32_e32 v86, s33, v0
	v_lshl_add_u64 v[84:85], v[84:85], 3, s[48:49]
	v_ashrrev_i32_e32 v87, 31, v86
	global_load_dwordx2 v[84:85], v[84:85], off
	v_lshl_add_u64 v[86:87], v[86:87], 3, s[48:49]
	global_load_dword v88, v[2:3], off
	global_load_dwordx2 v[86:87], v[86:87], off
	global_load_dwordx4 v[52:55], v[8:9], off offset:-256
	global_load_dwordx4 v[60:63], v[6:7], off offset:-256
	global_load_dwordx4 v[56:59], v[8:9], off offset:-240
	global_load_dwordx4 v[64:67], v[6:7], off offset:-240
	s_waitcnt vmcnt(2)
	v_lshlrev_b32_e32 v44, 16, v52
	ds_read_b128 v[34:37], v1
	ds_read_b128 v[38:41], v1 offset:16
	s_waitcnt lgkmcnt(1)
	v_pk_fma_f32 v[18:19], v[36:37], v[44:45], v[18:19] op_sel_hi:[1,0,1]
	v_pk_fma_f32 v[22:23], v[34:35], v[44:45], v[22:23] op_sel_hi:[1,0,1]
	s_waitcnt lgkmcnt(0)
	v_pk_fma_f32 v[24:25], v[38:39], v[44:45], v[24:25] op_sel_hi:[1,0,1]
	v_pk_fma_f32 v[20:21], v[40:41], v[44:45], v[20:21] op_sel_hi:[1,0,1]
	v_lshlrev_b32_e32 v48, 16, v60
	v_pk_fma_f32 v[36:37], v[36:37], v[48:49], v[10:11] op_sel_hi:[1,0,1]
	v_pk_fma_f32 v[34:35], v[34:35], v[48:49], v[14:15] op_sel_hi:[1,0,1]
	v_pk_fma_f32 v[38:39], v[38:39], v[48:49], v[16:17] op_sel_hi:[1,0,1]
	v_pk_fma_f32 v[40:41], v[40:41], v[48:49], v[12:13] op_sel_hi:[1,0,1]
	v_and_b32_e32 v44, 0xffff0000, v52
	v_and_b32_e32 v48, 0xffff0000, v60
	ds_read_b128 v[10:13], v1 offset:2048
	ds_read_b128 v[14:17], v1 offset:2064
	s_waitcnt lgkmcnt(1)
	v_pk_fma_f32 v[22:23], v[10:11], v[44:45], v[22:23] op_sel_hi:[1,0,1]
	v_pk_fma_f32 v[34:35], v[10:11], v[48:49], v[34:35] op_sel_hi:[1,0,1]
	s_waitcnt lgkmcnt(0)
	v_pk_fma_f32 v[24:25], v[14:15], v[44:45], v[24:25] op_sel_hi:[1,0,1]
	v_pk_fma_f32 v[18:19], v[12:13], v[44:45], v[18:19] op_sel_hi:[1,0,1]
	v_pk_fma_f32 v[20:21], v[16:17], v[44:45], v[20:21] op_sel_hi:[1,0,1]
	v_pk_fma_f32 v[38:39], v[14:15], v[48:49], v[38:39] op_sel_hi:[1,0,1]
	v_pk_fma_f32 v[36:37], v[12:13], v[48:49], v[36:37] op_sel_hi:[1,0,1]
	v_pk_fma_f32 v[40:41], v[16:17], v[48:49], v[40:41] op_sel_hi:[1,0,1]
	v_lshlrev_b32_e32 v44, 16, v53
	v_lshlrev_b32_e32 v48, 16, v61
	ds_read_b128 v[10:13], v1 offset:4096
	ds_read_b128 v[14:17], v1 offset:4112
	s_waitcnt lgkmcnt(1)
	v_pk_fma_f32 v[22:23], v[10:11], v[44:45], v[22:23] op_sel_hi:[1,0,1]
	v_pk_fma_f32 v[50:51], v[10:11], v[48:49], v[34:35] op_sel_hi:[1,0,1]
	s_waitcnt lgkmcnt(0)
	v_pk_fma_f32 v[24:25], v[14:15], v[44:45], v[24:25] op_sel_hi:[1,0,1]
	v_pk_fma_f32 v[18:19], v[12:13], v[44:45], v[18:19] op_sel_hi:[1,0,1]
	v_pk_fma_f32 v[20:21], v[16:17], v[44:45], v[20:21] op_sel_hi:[1,0,1]
	v_pk_fma_f32 v[44:45], v[12:13], v[48:49], v[36:37] op_sel_hi:[1,0,1]
	v_pk_fma_f32 v[38:39], v[14:15], v[48:49], v[38:39] op_sel_hi:[1,0,1]
	v_pk_fma_f32 v[40:41], v[16:17], v[48:49], v[40:41] op_sel_hi:[1,0,1]
	v_and_b32_e32 v42, 0xffff0000, v53
	v_and_b32_e32 v46, 0xffff0000, v61
	ds_read_b128 v[10:13], v1 offset:6144
	ds_read_b128 v[34:37], v1 offset:6160
	s_waitcnt lgkmcnt(1)
	v_pk_fma_f32 v[22:23], v[10:11], v[42:43], v[22:23] op_sel_hi:[1,0,1]
	s_waitcnt lgkmcnt(0)
	v_pk_fma_f32 v[24:25], v[34:35], v[42:43], v[24:25] op_sel_hi:[1,0,1]
	v_pk_fma_f32 v[14:15], v[10:11], v[46:47], v[50:51] op_sel_hi:[1,0,1]
	v_pk_fma_f32 v[16:17], v[34:35], v[46:47], v[38:39] op_sel_hi:[1,0,1]
	v_pk_fma_f32 v[18:19], v[12:13], v[42:43], v[18:19] op_sel_hi:[1,0,1]
	v_pk_fma_f32 v[20:21], v[36:37], v[42:43], v[20:21] op_sel_hi:[1,0,1]
	v_pk_fma_f32 v[10:11], v[12:13], v[46:47], v[44:45] op_sel_hi:[1,0,1]
	v_pk_fma_f32 v[12:13], v[36:37], v[46:47], v[40:41] op_sel_hi:[1,0,1]
	v_lshlrev_b32_e32 v44, 16, v54
	ds_read_b128 v[34:37], v1 offset:8192
	ds_read_b128 v[38:41], v1 offset:8208
	s_waitcnt lgkmcnt(1)
	v_pk_fma_f32 v[18:19], v[36:37], v[44:45], v[18:19] op_sel_hi:[1,0,1]
	v_pk_fma_f32 v[22:23], v[34:35], v[44:45], v[22:23] op_sel_hi:[1,0,1]
	s_waitcnt lgkmcnt(0)
	v_pk_fma_f32 v[24:25], v[38:39], v[44:45], v[24:25] op_sel_hi:[1,0,1]
	v_pk_fma_f32 v[20:21], v[40:41], v[44:45], v[20:21] op_sel_hi:[1,0,1]
	v_lshlrev_b32_e32 v48, 16, v62
	v_pk_fma_f32 v[36:37], v[36:37], v[48:49], v[10:11] op_sel_hi:[1,0,1]
	v_pk_fma_f32 v[34:35], v[34:35], v[48:49], v[14:15] op_sel_hi:[1,0,1]
	v_pk_fma_f32 v[38:39], v[38:39], v[48:49], v[16:17] op_sel_hi:[1,0,1]
	v_pk_fma_f32 v[40:41], v[40:41], v[48:49], v[12:13] op_sel_hi:[1,0,1]
	v_and_b32_e32 v44, 0xffff0000, v54
	v_and_b32_e32 v48, 0xffff0000, v62
	ds_read_b128 v[10:13], v1 offset:10240
	ds_read_b128 v[14:17], v1 offset:10256
	s_waitcnt lgkmcnt(1)
	v_pk_fma_f32 v[22:23], v[10:11], v[44:45], v[22:23] op_sel_hi:[1,0,1]
	v_pk_fma_f32 v[34:35], v[10:11], v[48:49], v[34:35] op_sel_hi:[1,0,1]
	s_waitcnt lgkmcnt(0)
	v_pk_fma_f32 v[24:25], v[14:15], v[44:45], v[24:25] op_sel_hi:[1,0,1]
	v_pk_fma_f32 v[18:19], v[12:13], v[44:45], v[18:19] op_sel_hi:[1,0,1]
	v_pk_fma_f32 v[20:21], v[16:17], v[44:45], v[20:21] op_sel_hi:[1,0,1]
	v_pk_fma_f32 v[38:39], v[14:15], v[48:49], v[38:39] op_sel_hi:[1,0,1]
	v_pk_fma_f32 v[36:37], v[12:13], v[48:49], v[36:37] op_sel_hi:[1,0,1]
	v_pk_fma_f32 v[40:41], v[16:17], v[48:49], v[40:41] op_sel_hi:[1,0,1]
	v_lshlrev_b32_e32 v44, 16, v55
	v_lshlrev_b32_e32 v48, 16, v63
	ds_read_b128 v[10:13], v1 offset:12288
	ds_read_b128 v[14:17], v1 offset:12304
	s_waitcnt lgkmcnt(1)
	v_pk_fma_f32 v[22:23], v[10:11], v[44:45], v[22:23] op_sel_hi:[1,0,1]
	v_pk_fma_f32 v[50:51], v[10:11], v[48:49], v[34:35] op_sel_hi:[1,0,1]
	s_waitcnt lgkmcnt(0)
; #define LAS __attribute__((address_space(3)))
; DI void gates_phase(LAS unsigned char* lds, const bf16_t* X, const ss_t* ss, const float* win  , const float* ng, const float* gbias, float* GATES, int G, int bid) {
;     ...
; #pragma unroll 4
;         for (int i = 0; i < 16; ++i) { const int k = lane + 64 * i; const float x0 = __builtin_bit_cast(float, (unsigned)xr0[k] << 16), x1 = __builtin_bit_cast(float, (unsigned)xr1[k] << 16); const f32x4 a = *(const LAS f32x4*)(wg + k * 8), b = *(const LAS f32x4*)(wg + k * 8 + 4);
; #pragma unroll
;             for (int e = 0; e < 4; ++e) { acc[0][e] += x0 * a[e]; acc[0][4 + e] += x0 * b[e]; acc[1][e] += x1 * a[e]; acc[1][4 + e] += x1 * b[e]; } }
	v_pk_fma_f32 v[24:25], v[14:15], v[44:45], v[24:25] op_sel_hi:[1,0,1]
	v_pk_fma_f32 v[18:19], v[12:13], v[44:45], v[18:19] op_sel_hi:[1,0,1]
	v_pk_fma_f32 v[20:21], v[16:17], v[44:45], v[20:21] op_sel_hi:[1,0,1]
	v_pk_fma_f32 v[44:45], v[12:13], v[48:49], v[36:37] op_sel_hi:[1,0,1]
	v_pk_fma_f32 v[38:39], v[14:15], v[48:49], v[38:39] op_sel_hi:[1,0,1]
	v_pk_fma_f32 v[40:41], v[16:17], v[48:49], v[40:41] op_sel_hi:[1,0,1]
	v_and_b32_e32 v42, 0xffff0000, v55
	v_and_b32_e32 v46, 0xffff0000, v63
	ds_read_b128 v[10:13], v1 offset:14336
	ds_read_b128 v[34:37], v1 offset:14352
	s_waitcnt lgkmcnt(1)
	v_pk_fma_f32 v[22:23], v[10:11], v[42:43], v[22:23] op_sel_hi:[1,0,1]
	s_waitcnt lgkmcnt(0)
	v_pk_fma_f32 v[24:25], v[34:35], v[42:43], v[24:25] op_sel_hi:[1,0,1]
	v_pk_fma_f32 v[14:15], v[10:11], v[46:47], v[50:51] op_sel_hi:[1,0,1]
	v_pk_fma_f32 v[16:17], v[34:35], v[46:47], v[38:39] op_sel_hi:[1,0,1]
	v_pk_fma_f32 v[18:19], v[12:13], v[42:43], v[18:19] op_sel_hi:[1,0,1]
	v_pk_fma_f32 v[20:21], v[36:37], v[42:43], v[20:21] op_sel_hi:[1,0,1]
	v_pk_fma_f32 v[10:11], v[12:13], v[46:47], v[44:45] op_sel_hi:[1,0,1]
	v_pk_fma_f32 v[12:13], v[36:37], v[46:47], v[40:41] op_sel_hi:[1,0,1]
	s_waitcnt vmcnt(0)
	v_lshlrev_b32_e32 v44, 16, v56
	ds_read_b128 v[34:37], v1 offset:16384
	ds_read_b128 v[38:41], v1 offset:16400
	s_waitcnt lgkmcnt(1)
	v_pk_fma_f32 v[18:19], v[36:37], v[44:45], v[18:19] op_sel_hi:[1,0,1]
	v_pk_fma_f32 v[22:23], v[34:35], v[44:45], v[22:23] op_sel_hi:[1,0,1]
	s_waitcnt lgkmcnt(0)
	v_pk_fma_f32 v[24:25], v[38:39], v[44:45], v[24:25] op_sel_hi:[1,0,1]
	v_pk_fma_f32 v[20:21], v[40:41], v[44:45], v[20:21] op_sel_hi:[1,0,1]
	v_lshlrev_b32_e32 v48, 16, v64
	v_pk_fma_f32 v[36:37], v[36:37], v[48:49], v[10:11] op_sel_hi:[1,0,1]
	v_pk_fma_f32 v[34:35], v[34:35], v[48:49], v[14:15] op_sel_hi:[1,0,1]
	v_pk_fma_f32 v[38:39], v[38:39], v[48:49], v[16:17] op_sel_hi:[1,0,1]
	v_pk_fma_f32 v[40:41], v[40:41], v[48:49], v[12:13] op_sel_hi:[1,0,1]
	v_and_b32_e32 v44, 0xffff0000, v56
	v_and_b32_e32 v48, 0xffff0000, v64
	ds_read_b128 v[10:13], v1 offset:18432
	ds_read_b128 v[14:17], v1 offset:18448
	s_waitcnt lgkmcnt(1)
	v_pk_fma_f32 v[22:23], v[10:11], v[44:45], v[22:23] op_sel_hi:[1,0,1]
	v_pk_fma_f32 v[34:35], v[10:11], v[48:49], v[34:35] op_sel_hi:[1,0,1]
	s_waitcnt lgkmcnt(0)
	v_pk_fma_f32 v[24:25], v[14:15], v[44:45], v[24:25] op_sel_hi:[1,0,1]
	v_pk_fma_f32 v[18:19], v[12:13], v[44:45], v[18:19] op_sel_hi:[1,0,1]
	v_pk_fma_f32 v[20:21], v[16:17], v[44:45], v[20:21] op_sel_hi:[1,0,1]
	v_pk_fma_f32 v[38:39], v[14:15], v[48:49], v[38:39] op_sel_hi:[1,0,1]
	v_pk_fma_f32 v[36:37], v[12:13], v[48:49], v[36:37] op_sel_hi:[1,0,1]
	v_pk_fma_f32 v[40:41], v[16:17], v[48:49], v[40:41] op_sel_hi:[1,0,1]
	v_lshlrev_b32_e32 v44, 16, v57
	v_lshlrev_b32_e32 v48, 16, v65
	ds_read_b128 v[10:13], v1 offset:20480
	ds_read_b128 v[14:17], v1 offset:20496
	s_waitcnt lgkmcnt(1)
	v_pk_fma_f32 v[22:23], v[10:11], v[44:45], v[22:23] op_sel_hi:[1,0,1]
	v_pk_fma_f32 v[50:51], v[10:11], v[48:49], v[34:35] op_sel_hi:[1,0,1]
	s_waitcnt lgkmcnt(0)
	v_pk_fma_f32 v[24:25], v[14:15], v[44:45], v[24:25] op_sel_hi:[1,0,1]
	v_pk_fma_f32 v[18:19], v[12:13], v[44:45], v[18:19] op_sel_hi:[1,0,1]
	v_pk_fma_f32 v[20:21], v[16:17], v[44:45], v[20:21] op_sel_hi:[1,0,1]
	v_pk_fma_f32 v[44:45], v[12:13], v[48:49], v[36:37] op_sel_hi:[1,0,1]
	v_pk_fma_f32 v[38:39], v[14:15], v[48:49], v[38:39] op_sel_hi:[1,0,1]
	v_pk_fma_f32 v[40:41], v[16:17], v[48:49], v[40:41] op_sel_hi:[1,0,1]
	v_and_b32_e32 v42, 0xffff0000, v57
	v_and_b32_e32 v46, 0xffff0000, v65
	ds_read_b128 v[10:13], v1 offset:22528
	ds_read_b128 v[34:37], v1 offset:22544
	s_waitcnt lgkmcnt(1)
	v_pk_fma_f32 v[22:23], v[10:11], v[42:43], v[22:23] op_sel_hi:[1,0,1]
	s_waitcnt lgkmcnt(0)
	v_pk_fma_f32 v[24:25], v[34:35], v[42:43], v[24:25] op_sel_hi:[1,0,1]
	v_pk_fma_f32 v[14:15], v[10:11], v[46:47], v[50:51] op_sel_hi:[1,0,1]
	v_pk_fma_f32 v[16:17], v[34:35], v[46:47], v[38:39] op_sel_hi:[1,0,1]
	v_pk_fma_f32 v[18:19], v[12:13], v[42:43], v[18:19] op_sel_hi:[1,0,1]
	v_pk_fma_f32 v[20:21], v[36:37], v[42:43], v[20:21] op_sel_hi:[1,0,1]
	v_pk_fma_f32 v[10:11], v[12:13], v[46:47], v[44:45] op_sel_hi:[1,0,1]
	v_pk_fma_f32 v[12:13], v[36:37], v[46:47], v[40:41] op_sel_hi:[1,0,1]
	v_lshlrev_b32_e32 v44, 16, v58
	ds_read_b128 v[34:37], v1 offset:24576
	ds_read_b128 v[38:41], v1 offset:24592
	s_waitcnt lgkmcnt(1)
	v_pk_fma_f32 v[18:19], v[36:37], v[44:45], v[18:19] op_sel_hi:[1,0,1]
	v_pk_fma_f32 v[22:23], v[34:35], v[44:45], v[22:23] op_sel_hi:[1,0,1]
	s_waitcnt lgkmcnt(0)
	v_pk_fma_f32 v[24:25], v[38:39], v[44:45], v[24:25] op_sel_hi:[1,0,1]
	v_pk_fma_f32 v[20:21], v[40:41], v[44:45], v[20:21] op_sel_hi:[1,0,1]
	v_lshlrev_b32_e32 v48, 16, v66
	v_pk_fma_f32 v[36:37], v[36:37], v[48:49], v[10:11] op_sel_hi:[1,0,1]
	v_pk_fma_f32 v[34:35], v[34:35], v[48:49], v[14:15] op_sel_hi:[1,0,1]
	v_pk_fma_f32 v[38:39], v[38:39], v[48:49], v[16:17] op_sel_hi:[1,0,1]
	v_pk_fma_f32 v[40:41], v[40:41], v[48:49], v[12:13] op_sel_hi:[1,0,1]
	v_and_b32_e32 v44, 0xffff0000, v58
	v_and_b32_e32 v48, 0xffff0000, v66
	ds_read_b128 v[10:13], v1 offset:26624
	ds_read_b128 v[14:17], v1 offset:26640
	s_waitcnt lgkmcnt(1)
	v_pk_fma_f32 v[22:23], v[10:11], v[44:45], v[22:23] op_sel_hi:[1,0,1]
	v_pk_fma_f32 v[34:35], v[10:11], v[48:49], v[34:35] op_sel_hi:[1,0,1]
	s_waitcnt lgkmcnt(0)
; #define LAS __attribute__((address_space(3)))
; DI float frsq(float x) { return __builtin_amdgcn_rsqf(x); }
; DI float ss_get(const ss_t* ss, int r) { return (float)ss[r] * (1.0f / 1048576.0f); }
; DI void gates_phase(LAS unsigned char* lds, const bf16_t* X, const ss_t* ss, const float* win  , const float* ng, const float* gbias, float* GATES, int G, int bid) {
;     ...
; #pragma unroll 4
;         for (int i = 0; i < 16; ++i) { const int k = lane + 64 * i; const float x0 = __builtin_bit_cast(float, (unsigned)xr0[k] << 16), x1 = __builtin_bit_cast(float, (unsigned)xr1[k] << 16); const f32x4 a = *(const LAS f32x4*)(wg + k * 8), b = *(const LAS f32x4*)(wg + k * 8 + 4);
; #pragma unroll
;             for (int e = 0; e < 4; ++e) { acc[0][e] += x0 * a[e]; acc[0][4 + e] += x0 * b[e]; acc[1][e] += x1 * a[e]; acc[1][4 + e] += x1 * b[e]; } }
; #pragma unroll
;         for (int r = 0; r < 2; ++r) {
;             float v4[4], v2[2], v1;
;             { const bool up = lane & 1;
; #pragma unroll
;               for (int e = 0; e < 4; ++e) { const float keep = up ? acc[r][4 + e] : acc[r][e], send = up ? acc[r][e] : acc[r][4 + e]; v4[e] = keep + __shfl_xor(send, 1); } }
;             { const bool up = lane & 2;
; #pragma unroll
;               for (int e = 0; e < 2; ++e) { const float keep = up ? v4[2 + e] : v4[e], send = up ? v4[e] : v4[2 + e]; v2[e] = keep + __shfl_xor(send, 2); } }
;             { const bool up = lane & 4; const float keep = up ? v2[1] : v2[0], send = up ? v2[0] : v2[1]; v1 = keep + __shfl_xor(send, 4); }
;             v1 += __shfl_xor(v1, 8); v1 += __shfl_xor(v1, 16); v1 += __shfl_xor(v1, 32);
;             const int m = m0 + r * NGW;
;             const float rs = frsq(ss_get(ss, m) * (1.0f / 1024.0f) + EPS);
;             if (lane < 8) { const int j = (lane & 1) * 4 + ((lane >> 1) & 1) * 2 + ((lane >> 2) & 1);
;                 float v = v1 * rs + gbias[j];
;                 if (j >= 4) v = fminf(v, 0.f) - log1pf(expf(-fabsf(v)));
;                 GATES[(size_t)m * 8 + j] = v; }
	v_pk_fma_f32 v[24:25], v[14:15], v[44:45], v[24:25] op_sel_hi:[1,0,1]
	v_pk_fma_f32 v[18:19], v[12:13], v[44:45], v[18:19] op_sel_hi:[1,0,1]
	v_pk_fma_f32 v[20:21], v[16:17], v[44:45], v[20:21] op_sel_hi:[1,0,1]
	v_pk_fma_f32 v[38:39], v[14:15], v[48:49], v[38:39] op_sel_hi:[1,0,1]
	v_pk_fma_f32 v[36:37], v[12:13], v[48:49], v[36:37] op_sel_hi:[1,0,1]
	v_pk_fma_f32 v[40:41], v[16:17], v[48:49], v[40:41] op_sel_hi:[1,0,1]
	v_lshlrev_b32_e32 v44, 16, v59
	v_lshlrev_b32_e32 v48, 16, v67
	ds_read_b128 v[10:13], v1 offset:28672
	ds_read_b128 v[14:17], v1 offset:28688
	s_waitcnt lgkmcnt(1)
	v_pk_fma_f32 v[22:23], v[10:11], v[44:45], v[22:23] op_sel_hi:[1,0,1]
	v_pk_fma_f32 v[50:51], v[10:11], v[48:49], v[34:35] op_sel_hi:[1,0,1]
	s_waitcnt lgkmcnt(0)
	v_pk_fma_f32 v[24:25], v[14:15], v[44:45], v[24:25] op_sel_hi:[1,0,1]
	v_pk_fma_f32 v[18:19], v[12:13], v[44:45], v[18:19] op_sel_hi:[1,0,1]
	v_pk_fma_f32 v[20:21], v[16:17], v[44:45], v[20:21] op_sel_hi:[1,0,1]
	v_pk_fma_f32 v[44:45], v[12:13], v[48:49], v[36:37] op_sel_hi:[1,0,1]
	v_pk_fma_f32 v[38:39], v[14:15], v[48:49], v[38:39] op_sel_hi:[1,0,1]
	v_pk_fma_f32 v[40:41], v[16:17], v[48:49], v[40:41] op_sel_hi:[1,0,1]
	v_and_b32_e32 v42, 0xffff0000, v59
	v_and_b32_e32 v46, 0xffff0000, v67
	ds_read_b128 v[10:13], v1 offset:30720
	ds_read_b128 v[34:37], v1 offset:30736
	s_waitcnt lgkmcnt(1)
	v_pk_fma_f32 v[22:23], v[10:11], v[42:43], v[22:23] op_sel_hi:[1,0,1]
	s_waitcnt lgkmcnt(0)
	v_pk_fma_f32 v[24:25], v[34:35], v[42:43], v[24:25] op_sel_hi:[1,0,1]
	v_pk_fma_f32 v[14:15], v[10:11], v[46:47], v[50:51] op_sel_hi:[1,0,1]
	v_pk_fma_f32 v[16:17], v[34:35], v[46:47], v[38:39] op_sel_hi:[1,0,1]
	v_pk_fma_f32 v[18:19], v[12:13], v[42:43], v[18:19] op_sel_hi:[1,0,1]
	v_pk_fma_f32 v[20:21], v[36:37], v[42:43], v[20:21] op_sel_hi:[1,0,1]
	v_pk_fma_f32 v[10:11], v[12:13], v[46:47], v[44:45] op_sel_hi:[1,0,1]
	v_pk_fma_f32 v[12:13], v[36:37], v[46:47], v[40:41] op_sel_hi:[1,0,1]
	v_cndmask_b32_e32 v33, v24, v22, vcc
	v_cndmask_b32_e32 v22, v22, v24, vcc
	v_cndmask_b32_e32 v24, v25, v23, vcc
	v_cndmask_b32_e32 v23, v23, v25, vcc
	ds_bpermute_b32 v23, v26, v23
	ds_bpermute_b32 v22, v26, v22
	v_ashrrev_i32_e32 v1, 31, v0
	s_waitcnt lgkmcnt(1)
	v_add_f32_e32 v23, v24, v23
	v_cndmask_b32_e32 v24, v20, v18, vcc
	v_cndmask_b32_e32 v18, v18, v20, vcc
	ds_bpermute_b32 v18, v26, v18
	v_cndmask_b32_e32 v20, v21, v19, vcc
	v_cndmask_b32_e32 v19, v19, v21, vcc
	ds_bpermute_b32 v19, v26, v19
	s_waitcnt lgkmcnt(2)
	v_add_f32_e32 v22, v33, v22
	s_waitcnt lgkmcnt(1)
	v_add_f32_e32 v18, v24, v18
	s_waitcnt lgkmcnt(0)
	v_add_f32_e32 v19, v20, v19
	v_cndmask_b32_e64 v20, v18, v22, s[38:39]
	v_cndmask_b32_e64 v18, v22, v18, s[38:39]
	ds_bpermute_b32 v18, v27, v18
	s_waitcnt lgkmcnt(0)
	v_add_f32_e32 v18, v20, v18
	v_cndmask_b32_e64 v20, v19, v23, s[38:39]
	v_cndmask_b32_e64 v19, v23, v19, s[38:39]
	ds_bpermute_b32 v19, v27, v19
	s_waitcnt lgkmcnt(0)
	v_add_f32_e32 v19, v20, v19
	v_cndmask_b32_e64 v20, v19, v18, s[40:41]
	v_cndmask_b32_e64 v18, v18, v19, s[40:41]
	ds_bpermute_b32 v18, v28, v18
	s_waitcnt lgkmcnt(0)
	v_add_f32_e32 v18, v20, v18
	ds_bpermute_b32 v19, v29, v18
	s_waitcnt lgkmcnt(0)
	v_add_f32_e32 v18, v18, v19
	ds_bpermute_b32 v19, v30, v18
	s_waitcnt lgkmcnt(0)
	v_add_f32_e32 v18, v18, v19
	ds_bpermute_b32 v19, v31, v18
	s_and_saveexec_b64 s[52:53], s[42:43]
	s_cbranch_execz .LBB0_451
	v_mov_b32_e32 v20, v84
	v_mov_b32_e32 v21, v85
	s_waitcnt lgkmcnt(0)
	v_add_f32_e32 v19, v18, v19
	v_mov_b32_e32 v18, v88
	v_xor_b32_e32 v22, v20, v21
	v_ashrrev_i32_e32 v22, 31, v22
	v_ffbh_i32_e32 v23, v21
	v_add_u32_e32 v22, 32, v22
	v_add_u32_e32 v23, -1, v23
	v_min_u32_e32 v22, v23, v22
	v_lshlrev_b64 v[20:21], v22, v[20:21]
	v_min_u32_e32 v20, 1, v20
	v_or_b32_e32 v20, v21, v20
	v_cvt_f32_i32_e32 v20, v20
	v_sub_u32_e32 v21, 32, v22
	v_ldexp_f32 v20, v20, v21
	v_mul_f32_e32 v20, 0x35800000, v20
	v_fmamk_f32 v20, v20, 0x3a800000, v229
	v_rsq_f32_e32 v20, v20
	s_nop 0
	v_fmac_f32_e32 v18, v19, v20
	s_and_saveexec_b64 s[54:55], s[44:45]
	s_cbranch_execz .LBB0_450
; DI void gates_phase(LAS unsigned char* lds, const bf16_t* X, const ss_t* ss, const float* win  , const float* ng, const float* gbias, float* GATES, int G, int bid) {
;     ...
;             if (lane < 8) { const int j = (lane & 1) * 4 + ((lane >> 1) & 1) * 2 + ((lane >> 2) & 1);
;                 float v = v1 * rs + gbias[j];
;                 if (j >= 4) v = fminf(v, 0.f) - log1pf(expf(-fabsf(v)));
;                 GATES[(size_t)m * 8 + j] = v; }
	s_mov_b32 s0, 0xbfb8aa3b
	v_mul_f32_e64 v19, |v18|, s0
	v_rndne_f32_e32 v20, v19
	v_sub_f32_e32 v21, v19, v20
	v_fma_f32 v19, |v18|, s0, -v19
	s_mov_b32 s0, 0xb2a5705f
	v_fma_f32 v19, |v18|, s0, v19
	v_add_f32_e32 v19, v21, v19
	v_exp_f32_e32 v19, v19
	v_cvt_i32_f32_e32 v20, v20
	s_mov_b32 s0, 0x42ce8ed0
	v_cmp_ngt_f32_e64 s[0:1], |v18|, s0
	v_max_f32_e32 v21, v18, v18
	v_ldexp_f32 v19, v19, v20
	v_cndmask_b32_e64 v19, 0, v19, s[0:1]
	s_mov_b32 s0, 0xc2b17218
	v_cmp_nlt_f32_e64 s[0:1], |v18|, s0
	v_min_f32_e32 v33, 0, v21
	s_nop 0
	v_cndmask_b32_e64 v40, v236, v19, s[0:1]
	v_add_f32_e32 v20, 1.0, v40
	v_add_f32_e32 v18, -1.0, v20
	v_sub_f32_e32 v19, v18, v20
	v_add_f32_e32 v19, 1.0, v19
	v_sub_f32_e32 v18, v40, v18
	v_add_f32_e32 v21, v18, v19
	v_frexp_mant_f32_e32 v22, v20
	v_cvt_f64_f32_e32 v[18:19], v20
	s_mov_b32 s0, 0x3f2aaaab
	v_frexp_exp_i32_f64_e32 v18, v[18:19]
	v_cmp_gt_f32_e64 s[0:1], s0, v22
	s_nop 1
	v_subbrev_co_u32_e64 v34, s[0:1], 0, v18, s[0:1]
	v_sub_u32_e32 v18, 0, v34
	v_ldexp_f32 v19, v20, v18
	v_add_f32_e32 v20, -1.0, v19
	v_add_f32_e32 v22, 1.0, v19
	v_ldexp_f32 v18, v21, v18
	v_add_f32_e32 v21, 1.0, v20
	v_add_f32_e32 v23, -1.0, v22
	v_sub_f32_e32 v21, v19, v21
	v_sub_f32_e32 v19, v19, v23
	v_add_f32_e32 v21, v18, v21
	v_add_f32_e32 v18, v18, v19
	v_add_f32_e32 v35, v22, v18
	v_rcp_f32_e32 v37, v35
	v_sub_f32_e32 v19, v22, v35
	v_add_f32_e32 v36, v18, v19
	v_add_f32_e32 v19, v20, v21
	v_mul_f32_e32 v39, v19, v37
	v_sub_f32_e32 v18, v20, v19
	v_mul_f32_e32 v20, v35, v39
	v_fma_f32 v22, v39, v35, -v20
	v_fmac_f32_e32 v22, v39, v36
	v_add_f32_e32 v38, v21, v18
	v_add_f32_e32 v18, v20, v22
	v_sub_f32_e32 v21, v19, v18
	v_pk_add_f32 v[24:25], v[18:19], v[20:21] neg_lo:[0,1] neg_hi:[0,1]
	v_mov_b32_e32 v23, v18
	v_pk_add_f32 v[18:19], v[24:25], v[22:23] neg_lo:[0,1] neg_hi:[0,1]
	s_mov_b32 s0, 0x3f317218
	v_add_f32_e32 v19, v38, v19
	v_add_f32_e32 v18, v18, v19
	v_add_f32_e32 v19, v21, v18
	v_mul_f32_e32 v38, v37, v19
	v_mul_f32_e32 v20, v35, v38
	v_fma_f32 v22, v38, v35, -v20
	v_fmac_f32_e32 v22, v38, v36
	v_sub_f32_e32 v21, v21, v19
	v_add_f32_e32 v35, v18, v21
	v_add_f32_e32 v18, v20, v22
	v_sub_f32_e32 v21, v19, v18
	v_pk_add_f32 v[24:25], v[18:19], v[20:21] neg_lo:[0,1] neg_hi:[0,1]
	v_mov_b32_e32 v23, v18
	v_pk_add_f32 v[18:19], v[24:25], v[22:23] neg_lo:[0,1] neg_hi:[0,1]
	s_nop 0
	v_add_f32_e32 v19, v35, v19
	v_add_f32_e32 v18, v18, v19
	v_add_f32_e32 v19, v39, v38
	v_add_f32_e32 v18, v21, v18
	v_sub_f32_e32 v20, v19, v39
	v_mul_f32_e32 v18, v37, v18
	v_sub_f32_e32 v20, v38, v20
	v_add_f32_e32 v20, v20, v18
	v_add_f32_e32 v22, v19, v20
	v_mul_f32_e32 v23, v22, v22
	v_fmamk_f32 v18, v23, 0x3e9b6dac, v230
	v_fmaak_f32 v191, v23, v18, 0x3f2aaada
	v_cvt_f32_i32_e32 v18, v34
	v_sub_f32_e32 v19, v22, v19
	v_sub_f32_e32 v19, v20, v19
	v_ldexp_f32 v24, v19, 1
	v_mul_f32_e32 v19, v22, v23
	v_ldexp_f32 v21, v22, 1
	v_pk_mul_f32 v[22:23], v[18:19], v[190:191]
	s_nop 0
	v_fma_f32 v20, v18, s0, -v22
	v_fmac_f32_e32 v20, 0xb102e308, v18
	v_pk_add_f32 v[18:19], v[22:23], v[20:21]
	s_mov_b32 s0, 0x7f800000
	v_sub_f32_e32 v21, v19, v21
	v_sub_f32_e32 v21, v23, v21
	v_add_f32_e32 v25, v24, v21
	v_mov_b32_e32 v24, v22
	v_pk_add_f32 v[22:23], v[18:19], v[22:23] neg_lo:[0,1] neg_hi:[0,1]
	v_pk_add_f32 v[34:35], v[18:19], v[24:25]
	v_mov_b32_e32 v21, v18
	v_mov_b32_e32 v23, v35
	v_pk_add_f32 v[36:37], v[20:21], v[22:23] neg_lo:[0,1] neg_hi:[0,1]
	v_pk_add_f32 v[20:21], v[20:21], v[22:23]
	v_mov_b32_e32 v24, v25
	v_pk_add_f32 v[22:23], v[20:21], v[18:19] op_sel:[1,0] op_sel_hi:[0,1] neg_lo:[0,1] neg_hi:[0,1]
	v_pk_add_f32 v[38:39], v[34:35], v[22:23] op_sel_hi:[1,0] neg_lo:[0,1] neg_hi:[0,1]
	v_mov_b32_e32 v34, v35
	v_mov_b32_e32 v35, v21
	v_pk_mov_b32 v[22:23], v[18:19], v[22:23] op_sel:[1,0]
	v_mov_b32_e32 v25, v18
	v_pk_add_f32 v[22:23], v[34:35], v[22:23] neg_lo:[0,1] neg_hi:[0,1]
	v_mov_b32_e32 v38, v36
	v_pk_add_f32 v[18:19], v[24:25], v[22:23] neg_lo:[0,1] neg_hi:[0,1]
	v_mov_b32_e32 v37, v21
	v_pk_add_f32 v[22:23], v[38:39], v[18:19]
	v_cmp_neq_f32_e64 s[0:1], s0, v40
	v_pk_add_f32 v[24:25], v[22:23], v[22:23] op_sel:[0,1] op_sel_hi:[1,0]
	s_nop 0
	v_pk_add_f32 v[20:21], v[20:21], v[24:25] op_sel:[1,0] op_sel_hi:[0,1]
	v_mov_b32_e32 v23, v20
	v_pk_add_f32 v[34:35], v[22:23], v[36:37] neg_lo:[0,1] neg_hi:[0,1]
	v_mov_b32_e32 v19, v24
	v_sub_f32_e32 v21, v22, v34
	v_pk_add_f32 v[18:19], v[18:19], v[34:35] neg_lo:[0,1] neg_hi:[0,1]
	v_sub_f32_e32 v21, v36, v21
	v_add_f32_e32 v18, v18, v21
	v_add_f32_e32 v18, v18, v19
	v_add_f32_e32 v18, v20, v18
	v_cndmask_b32_e64 v18, v236, v18, s[0:1]
	s_mov_b32 s0, 0x33800000
	v_cmp_lt_f32_e64 s[0:1], |v40|, s0
	s_nop 1
	v_cndmask_b32_e64 v18, v18, v40, s[0:1]
	v_sub_f32_e32 v18, v33, v18
